# LRU tile loop: L2 prefetch of the next tile's conv input rows (7 dword touches per thread) after the tile's last vmcnt wait
# speedup vs baseline: 1.0341x; 1.0083x over previous
; DI float bflo(unsigned w) { return __uint_as_float(w << 16); }
; DI float bfhi(unsigned w) { return __uint_as_float(w & 0xffff0000u); }
; DI void lru_tile(const Params& p, unsigned char* shm, int c, int nb, const LruPar par) {
;     ...
;         float xr[7][8];
; #pragma unroll
;         for (int k = 0; k < 7; ++k) { const int t = c * 128 + rg * 4 - 2 + k;
;             u32x4 v = {0u, 0u, 0u, 0u};
;             if (t >= 0 && t < S) v = *(const u32x4*)(ZU + (size_t)(nb >> 1) * S * 256 + (size_t)t * 256 + (nb & 1) * 128 + cgp * 8);
; #pragma unroll
;             for (int i = 0; i < 4; ++i) { xr[k][2 * i] = bflo(v[i]); xr[k][2 * i + 1] = bfhi(v[i]); } }
.LBB0_218:
	s_or_b64 exec, exec, s[4:5]
	v_cmp_gt_u32_e32 vcc, s65, v64
	v_mov_b32_e32 v52, 0
	v_lshlrev_b32_e32 v68, 9, v64
	v_add_u32_e32 v250, 0x100000, v68
	v_mov_b32_e32 v251, 0
	v_lshl_add_u64 v[248:249], v[96:97], 0, v[250:251]
	v_mov_b32_e32 v48, 0
	v_mov_b32_e32 v49, 0
	v_mov_b32_e32 v50, 0
	v_mov_b32_e32 v51, 0
	s_and_saveexec_b64 s[4:5], vcc
	s_cbranch_execz .LBB0_220
	v_lshl_add_u64 v[48:49], v[96:97], 0, v[68:69]
	global_load_dwordx4 v[48:51], v[48:49], off

; DI void lru_tile(const Params& p, unsigned char* shm, int c, int nb, const LruPar par) {
;     ...
;         bf16x8 bfr[4][2];
; #pragma unroll
;         for (int s = 0; s < 4; ++s)
; #pragma unroll
;             for (int gt = 0; gt < 2; ++gt) bfr[s][gt] = *(const bf16x8*)(LWT + ((size_t)((d * 2 + gt) * 16 + nb) * 128 + chl) * 128 + s * 32 + q * 8);
; #pragma unroll
;         for (int s = 0; s < 4; ++s) {
; #pragma unroll
;             for (int rt = 0; rt < 8; ++rt) {
;                 const bf16x8 af = *(const bf16x8*)(UB + (rt * 16 + col) * LDU + s * 32 + q * 8);
; #pragma unroll
;                 for (int gt = 0; gt < 2; ++gt) acc[gt][rt] = __builtin_amdgcn_mfma_f32_16x16x32_bf16(af, bfr[s][gt], acc[gt][rt], 0, 0, 0);
;             }
;             __builtin_amdgcn_sched_barrier(0);
;         }
.LBB0_230:
	s_or_b64 exec, exec, s[60:61]
	v_mul_u32_u24_e32 v4, 0x110, v164
	s_or_b32 s60, s38, 0x1000
	s_mov_b32 s61, s39
	v_lshl_add_u64 v[0:1], v[48:49], 0, s[60:61]
	s_or_b32 s60, s38, 0x1800
	v_lshlrev_b64 v[0:1], 8, v[0:1]
	v_lshl_add_u64 v[12:13], v[48:49], 0, s[60:61]
	v_lshl_add_u64 v[176:177], v[160:161], 0, v[0:1]
	v_lshlrev_b64 v[12:13], 8, v[12:13]
	global_load_dwordx4 v[0:3], v[176:177], off
	v_add_u32_e32 v79, v165, v4
	v_lshl_add_u64 v[160:161], v[160:161], 0, v[12:13]
	ds_read_b128 v[4:7], v79
	ds_read_b128 v[8:11], v79 offset:4352
	global_load_dwordx4 v[12:15], v[176:177], off offset:64
	global_load_dwordx4 v[20:23], v[160:161], off
	global_load_dwordx4 v[24:27], v[160:161], off offset:64
	ds_read_b128 v[32:35], v79 offset:8704
	ds_read_b128 v[36:39], v79 offset:13056
	ds_read_b128 v[164:167], v79 offset:17408
	ds_read_b128 v[168:171], v79 offset:21760
	ds_read_b128 v[212:215], v79 offset:26112
	ds_read_b128 v[216:219], v79 offset:30464
	global_load_dwordx4 v[224:227], v[176:177], off offset:128
	global_load_dwordx4 v[228:231], v[176:177], off offset:192
	global_load_dwordx4 v[232:235], v[160:161], off offset:128
	global_load_dwordx4 v[236:239], v[160:161], off offset:192
	s_waitcnt vmcnt(7) lgkmcnt(7)
	v_mfma_f32_16x16x32_bf16 v[16:19], v[4:7], v[0:3], 0
	s_waitcnt vmcnt(5)
	v_mfma_f32_16x16x32_bf16 v[4:7], v[4:7], v[20:23], 0
	s_waitcnt lgkmcnt(6)
	v_mfma_f32_16x16x32_bf16 v[28:31], v[8:11], v[0:3], 0
	v_mfma_f32_16x16x32_bf16 v[8:11], v[8:11], v[20:23], 0
	s_waitcnt lgkmcnt(5)
	v_mfma_f32_16x16x32_bf16 v[40:43], v[32:35], v[0:3], 0
	v_mfma_f32_16x16x32_bf16 v[32:35], v[32:35], v[20:23], 0
	s_waitcnt lgkmcnt(4)
	v_mfma_f32_16x16x32_bf16 v[44:47], v[36:39], v[0:3], 0
	v_mfma_f32_16x16x32_bf16 v[36:39], v[36:39], v[20:23], 0
	s_waitcnt lgkmcnt(3)
	v_mfma_f32_16x16x32_bf16 v[172:175], v[164:167], v[0:3], 0
	v_mfma_f32_16x16x32_bf16 v[164:167], v[164:167], v[20:23], 0
	s_waitcnt lgkmcnt(2)
	v_mfma_f32_16x16x32_bf16 v[208:211], v[168:171], v[0:3], 0
	v_mfma_f32_16x16x32_bf16 v[168:171], v[168:171], v[20:23], 0
	s_waitcnt lgkmcnt(1)
	v_mfma_f32_16x16x32_bf16 v[220:223], v[212:215], v[0:3], 0
	v_mfma_f32_16x16x32_bf16 v[212:215], v[212:215], v[20:23], 0
	s_waitcnt lgkmcnt(0)
	v_mfma_f32_16x16x32_bf16 v[0:3], v[216:219], v[0:3], 0
	v_mfma_f32_16x16x32_bf16 v[20:23], v[216:219], v[20:23], 0
	ds_read_b128 v[216:219], v79 offset:64
	ds_read_b128 v[240:243], v79 offset:4416
	s_waitcnt lgkmcnt(1)
	v_mfma_f32_16x16x32_bf16 v[16:19], v[216:219], v[12:15], v[16:19]
	s_waitcnt vmcnt(4)
	v_mfma_f32_16x16x32_bf16 v[4:7], v[216:219], v[24:27], v[4:7]
	s_waitcnt lgkmcnt(0)
	v_mfma_f32_16x16x32_bf16 v[28:31], v[240:243], v[12:15], v[28:31]
	v_mfma_f32_16x16x32_bf16 v[8:11], v[240:243], v[24:27], v[8:11]
	ds_read_b128 v[216:219], v79 offset:8768
	ds_read_b128 v[240:243], v79 offset:13120
	s_waitcnt lgkmcnt(1)
	v_mfma_f32_16x16x32_bf16 v[40:43], v[216:219], v[12:15], v[40:43]
	v_mfma_f32_16x16x32_bf16 v[32:35], v[216:219], v[24:27], v[32:35]
	s_waitcnt lgkmcnt(0)
	v_mfma_f32_16x16x32_bf16 v[44:47], v[240:243], v[12:15], v[44:47]
	v_mfma_f32_16x16x32_bf16 v[36:39], v[240:243], v[24:27], v[36:39]
	ds_read_b128 v[216:219], v79 offset:17472
	ds_read_b128 v[240:243], v79 offset:21824
	s_waitcnt lgkmcnt(1)
	v_mfma_f32_16x16x32_bf16 v[172:175], v[216:219], v[12:15], v[172:175]
	v_mfma_f32_16x16x32_bf16 v[164:167], v[216:219], v[24:27], v[164:167]
	s_waitcnt lgkmcnt(0)
	v_mfma_f32_16x16x32_bf16 v[208:211], v[240:243], v[12:15], v[208:211]
	v_mfma_f32_16x16x32_bf16 v[168:171], v[240:243], v[24:27], v[168:171]
	ds_read_b128 v[216:219], v79 offset:26176
	ds_read_b128 v[240:243], v79 offset:30528
	s_waitcnt lgkmcnt(1)
	v_mfma_f32_16x16x32_bf16 v[220:223], v[216:219], v[12:15], v[220:223]
	v_mfma_f32_16x16x32_bf16 v[212:215], v[216:219], v[24:27], v[212:215]
	s_waitcnt lgkmcnt(0)
	v_mfma_f32_16x16x32_bf16 v[0:3], v[240:243], v[12:15], v[0:3]
	v_mfma_f32_16x16x32_bf16 v[12:15], v[240:243], v[24:27], v[20:23]
	s_nop 2
	ds_read_b128 v[20:23], v79 offset:128
	ds_read_b128 v[24:27], v79 offset:4480
	s_waitcnt vmcnt(3) lgkmcnt(1)
	v_mfma_f32_16x16x32_bf16 v[16:19], v[20:23], v[224:227], v[16:19]
	s_waitcnt vmcnt(1)
	v_mfma_f32_16x16x32_bf16 v[4:7], v[20:23], v[232:235], v[4:7]
	s_waitcnt lgkmcnt(0)
	v_mfma_f32_16x16x32_bf16 v[20:23], v[24:27], v[224:227], v[28:31]
	v_mfma_f32_16x16x32_bf16 v[8:11], v[24:27], v[232:235], v[8:11]
	ds_read_b128 v[24:27], v79 offset:8832
	s_nop 0
	ds_read_b128 v[28:31], v79 offset:13184
	s_waitcnt lgkmcnt(1)
	v_mfma_f32_16x16x32_bf16 v[40:43], v[24:27], v[224:227], v[40:43]
	v_mfma_f32_16x16x32_bf16 v[24:27], v[24:27], v[232:235], v[32:35]
	s_waitcnt lgkmcnt(0)
	v_mfma_f32_16x16x32_bf16 v[32:35], v[28:31], v[224:227], v[44:47]
	v_mfma_f32_16x16x32_bf16 v[28:31], v[28:31], v[232:235], v[36:39]
	s_nop 2
	ds_read_b128 v[36:39], v79 offset:17536
	ds_read_b128 v[44:47], v79 offset:21888
	s_waitcnt lgkmcnt(1)
	v_mfma_f32_16x16x32_bf16 v[172:175], v[36:39], v[224:227], v[172:175]
	v_mfma_f32_16x16x32_bf16 v[164:167], v[36:39], v[232:235], v[164:167]
	s_waitcnt lgkmcnt(0)
	v_mfma_f32_16x16x32_bf16 v[208:211], v[44:47], v[224:227], v[208:211]
	v_mfma_f32_16x16x32_bf16 v[168:171], v[44:47], v[232:235], v[168:171]
	ds_read_b128 v[36:39], v79 offset:26240
	ds_read_b128 v[44:47], v79 offset:30592
	s_waitcnt lgkmcnt(1)
	v_mfma_f32_16x16x32_bf16 v[216:219], v[36:39], v[224:227], v[220:223]
	v_mfma_f32_16x16x32_bf16 v[212:215], v[36:39], v[232:235], v[212:215]
	s_waitcnt lgkmcnt(0)
	v_mfma_f32_16x16x32_bf16 v[0:3], v[44:47], v[224:227], v[0:3]
	v_mfma_f32_16x16x32_bf16 v[220:223], v[44:47], v[232:235], v[12:15]
	s_nop 2
	ds_read_b128 v[12:15], v79 offset:192
	ds_read_b128 v[36:39], v79 offset:4544
	s_waitcnt vmcnt(0) lgkmcnt(1)
; DI float bf2f(unsigned short b) { return __uint_as_float(((unsigned)b) << 16); }
; DI float ex2(float x) { return __builtin_amdgcn_exp2f(x); }
; DI float rcpf_(float x) { return __builtin_amdgcn_rcpf(x); }
; DI void lru_tile(const Params& p, unsigned char* shm, int c, int nb, const LruPar par) {
;     ...
;         for (int s = 0; s < 4; ++s) {
; #pragma unroll
;             for (int rt = 0; rt < 8; ++rt) {
;                 const bf16x8 af = *(const bf16x8*)(UB + (rt * 16 + col) * LDU + s * 32 + q * 8);
; #pragma unroll
;                 for (int gt = 0; gt < 2; ++gt) acc[gt][rt] = __builtin_amdgcn_mfma_f32_16x16x32_bf16(af, bfr[s][gt], acc[gt][rt], 0, 0, 0);
;             }
;             __builtin_amdgcn_sched_barrier(0);
;         }
;         const f32x2 nl2 = {-LOG2E, -LOG2E}, nbr2 = {par.nbr[d], par.nbr[d]}, nbi2 = {par.nbi[d], par.nbi[d]}, cd2 = {par.cdec[d], par.cdec[d]}, one2 = {1.f, 1.f};
;         float hl[8][4], pc[8][4];
; #pragma unroll
;         for (int rt = 0; rt < 8; ++rt) {
;             float av[4], bv[4];
; #pragma unroll
;             for (int jp = 0; jp < 2; ++jp) {
;                 const f32x2 xr = {acc[0][rt][2 * jp], acc[0][rt][2 * jp + 1]}, xi = {acc[1][rt][2 * jp], acc[1][rt][2 * jp + 1]};
;                 f32x2 er = xr * nl2 + nbr2, ei = xi * nl2 + nbi2;
;                 er = (f32x2){ex2(er[0]), ex2(er[1])} + one2; ei = (f32x2){ex2(ei[0]), ex2(ei[1])} + one2;
;                 const f32x2 r = {rcpf_(er[0]), rcpf_(er[1])}, ig = {rcpf_(ei[0]), rcpf_(ei[1])};
;                 const f32x2 la = r * cd2;
;                 const f32x2 a = {ex2(la[0]), ex2(la[1])};
;                 const f32x2 om = one2 - a * a;
;                 const f32x2 sc = {__builtin_amdgcn_sqrtf(om[0]), __builtin_amdgcn_sqrtf(om[1])};
;                 const f32x2 u2 = {bf2f(UB[(rt * 16 + 4 * q + 2 * jp) * LDU + chl]), bf2f(UB[(rt * 16 + 4 * q + 2 * jp + 1) * LDU + chl])};
;                 const f32x2 b2 = sc * ig * u2;
;                 av[2 * jp] = a[0]; av[2 * jp + 1] = a[1]; bv[2 * jp] = b2[0]; bv[2 * jp + 1] = b2[1];
;             }
	global_load_dword v252, v[248:249], off offset:-1024
	global_load_dword v253, v[248:249], off offset:-512
	global_load_dword v254, v[248:249], off
	global_load_dword v255, v[248:249], off offset:512
	global_load_dword v252, v[248:249], off offset:1024
	global_load_dword v253, v[248:249], off offset:1536
	global_load_dword v254, v[248:249], off offset:2048
	v_mfma_f32_16x16x32_bf16 v[232:235], v[12:15], v[236:239], v[4:7]
	s_waitcnt lgkmcnt(0)
	v_mfma_f32_16x16x32_bf16 v[244:247], v[36:39], v[236:239], v[8:11]
	s_nop 0
	ds_read_b128 v[4:7], v79 offset:8896
	s_nop 0
	ds_read_b128 v[8:11], v79 offset:13248
	v_mfma_f32_16x16x32_bf16 v[240:243], v[36:39], v[228:231], v[20:23]
	s_waitcnt lgkmcnt(1)
	v_mfma_f32_16x16x32_bf16 v[44:47], v[4:7], v[228:231], v[40:43]
	v_mfma_f32_16x16x32_bf16 v[40:43], v[4:7], v[236:239], v[24:27]
	s_waitcnt lgkmcnt(0)
	v_mfma_f32_16x16x32_bf16 v[36:39], v[8:11], v[228:231], v[32:35]
	v_mfma_f32_16x16x32_bf16 v[32:35], v[8:11], v[236:239], v[28:31]
	ds_read_b128 v[4:7], v79 offset:17600
	ds_read_b128 v[8:11], v79 offset:21952
	s_waitcnt lgkmcnt(1)
	v_mfma_f32_16x16x32_bf16 v[28:31], v[4:7], v[228:231], v[172:175]
	v_mfma_f32_16x16x32_bf16 v[24:27], v[4:7], v[236:239], v[164:167]
	ds_read_b128 v[4:7], v79 offset:26304
	s_nop 1
	ds_read_b128 v[164:167], v79 offset:30656
	v_mfma_f32_16x16x32_bf16 v[224:227], v[12:15], v[228:231], v[16:19]
	s_waitcnt lgkmcnt(2)
	v_mfma_f32_16x16x32_bf16 v[20:23], v[8:11], v[228:231], v[208:211]
	v_mfma_f32_16x16x32_bf16 v[16:19], v[8:11], v[236:239], v[168:171]
	s_waitcnt lgkmcnt(1)
	v_mfma_f32_16x16x32_bf16 v[12:15], v[4:7], v[228:231], v[216:219]
	v_mfma_f32_16x16x32_bf16 v[8:11], v[4:7], v[236:239], v[212:215]
	s_waitcnt lgkmcnt(0)
	v_mfma_f32_16x16x32_bf16 v[4:7], v[164:167], v[228:231], v[0:3]
	v_mfma_f32_16x16x32_bf16 v[0:3], v[164:167], v[236:239], v[220:223]
	v_fma_f32 v160, -v226, s50, v83
	v_fma_f32 v161, -v227, s50, v83
	v_pk_fma_f32 v[164:165], v[234:235], s[50:51], v[86:87] op_sel:[0,0,1] op_sel_hi:[1,0,1] neg_lo:[1,0,0] neg_hi:[1,0,0]
	v_exp_f32_e32 v160, v160
	v_exp_f32_e32 v161, v161
	v_exp_f32_e32 v164, v164
	v_exp_f32_e32 v165, v165
	v_pk_fma_f32 v[168:169], v[224:225], s[50:51], v[82:83] op_sel:[0,0,1] op_sel_hi:[1,0,1] neg_lo:[1,0,0] neg_hi:[1,0,0]
	v_pk_add_f32 v[160:161], v[160:161], 1.0 op_sel_hi:[1,0]
	v_exp_f32_e32 v168, v168
	v_rcp_f32_e32 v160, v160
	v_rcp_f32_e32 v161, v161
	v_pk_add_f32 v[164:165], v[164:165], 1.0 op_sel_hi:[1,0]
	v_exp_f32_e32 v169, v169
	v_rcp_f32_e32 v164, v164
	v_pk_mul_f32 v[160:161], v[92:93], v[160:161] op_sel:[1,0]
	v_rcp_f32_e32 v165, v165
	v_exp_f32_e32 v161, v161
	v_exp_f32_e32 v160, v160
	ds_read_u16 v49, v68 offset:544
	ds_read_u16 v79, v97 offset:816
	ds_read_u16 v81, v97 offset:272
	ds_read_u16 v85, v68
	v_pk_fma_f32 v[166:167], v[160:161], v[160:161], 1.0 op_sel_hi:[1,1,0] neg_lo:[1,0,0] neg_hi:[1,0,0]
	s_nop 0
	v_sqrt_f32_e32 v166, v166
	v_sqrt_f32_e32 v167, v167
	s_nop 0
	v_pk_mul_f32 v[164:165], v[164:165], v[166:167]
	v_pk_add_f32 v[166:167], v[168:169], 1.0 op_sel_hi:[1,0]
	v_pk_fma_f32 v[168:169], v[232:233], s[50:51], v[86:87] op_sel:[0,0,1] op_sel_hi:[1,0,1] neg_lo:[1,0,0] neg_hi:[1,0,0]
	v_rcp_f32_e32 v166, v166
	v_rcp_f32_e32 v167, v167
	v_exp_f32_e32 v168, v168
	v_exp_f32_e32 v169, v169
	v_pk_mul_f32 v[166:167], v[92:93], v[166:167] op_sel:[1,0]
	s_nop 0
	v_exp_f32_e32 v170, v166
	v_exp_f32_e32 v171, v167
	v_pk_add_f32 v[166:167], v[168:169], 1.0 op_sel_hi:[1,0]
	s_nop 0
	v_rcp_f32_e32 v168, v166
	v_rcp_f32_e32 v169, v167
	v_pk_fma_f32 v[166:167], v[170:171], v[170:171], 1.0 op_sel_hi:[1,1,0] neg_lo:[1,0,0] neg_hi:[1,0,0]
	s_nop 0
	v_sqrt_f32_e32 v172, v166
	v_sqrt_f32_e32 v173, v167
	s_waitcnt lgkmcnt(3)
	v_lshlrev_b32_e32 v166, 16, v49
	s_waitcnt lgkmcnt(2)
	v_lshlrev_b32_e32 v167, 16, v79
	v_pk_mul_f32 v[166:167], v[164:165], v[166:167]
	v_pk_mul_f32 v[164:165], v[168:169], v[172:173]
	s_waitcnt lgkmcnt(0)
	v_lshlrev_b32_e32 v168, 16, v85
	v_lshlrev_b32_e32 v169, 16, v81
	v_fma_f32 v167, 0, v161, v167
	v_pk_mul_f32 v[168:169], v[164:165], v[168:169]
	v_fmac_f32_e32 v166, v160, v167
	v_mul_f32_e32 v160, v161, v160
	v_fma_f32 v169, v171, v166, v169
	v_mul_f32_e32 v49, v171, v160
	v_fmac_f32_e32 v168, v170, v169
	v_mul_f32_e32 v170, v170, v49
	v_mov_b32_e32 v171, v168
	ds_write_b64 v61, v[170:171]
	v_pk_fma_f32 v[164:165], v[242:243], s[50:51], v[82:83] op_sel:[0,0,1] op_sel_hi:[1,0,1] neg_lo:[1,0,0] neg_hi:[1,0,0]
	v_pk_fma_f32 v[172:173], v[246:247], s[50:51], v[86:87] op_sel:[0,0,1] op_sel_hi:[1,0,1] neg_lo:[1,0,0] neg_hi:[1,0,0]
	v_exp_f32_e32 v164, v164
	v_exp_f32_e32 v165, v165
	v_exp_f32_e32 v172, v172
	v_exp_f32_e32 v173, v173
	v_pk_fma_f32 v[176:177], v[240:241], s[50:51], v[82:83] op_sel:[0,0,1] op_sel_hi:[1,0,1] neg_lo:[1,0,0] neg_hi:[1,0,0]
	v_pk_add_f32 v[164:165], v[164:165], 1.0 op_sel_hi:[1,0]
	v_exp_f32_e32 v176, v176
	v_rcp_f32_e32 v164, v164
	v_rcp_f32_e32 v165, v165
	v_pk_add_f32 v[172:173], v[172:173], 1.0 op_sel_hi:[1,0]
	v_exp_f32_e32 v177, v177
	v_rcp_f32_e32 v172, v172
	v_pk_mul_f32 v[164:165], v[92:93], v[164:165] op_sel:[1,0]
	v_rcp_f32_e32 v173, v173
	v_exp_f32_e32 v165, v165
	v_exp_f32_e32 v164, v164
	ds_read_u16 v79, v68 offset:4896
	ds_read_u16 v81, v97 offset:5168
	ds_read_u16 v85, v97 offset:4624
	ds_read_u16 v91, v68 offset:4352
	v_pk_fma_f32 v[174:175], v[164:165], v[164:165], 1.0 op_sel_hi:[1,1,0] neg_lo:[1,0,0] neg_hi:[1,0,0]
	s_nop 0
	v_sqrt_f32_e32 v174, v174
	v_sqrt_f32_e32 v175, v175
	s_waitcnt lgkmcnt(3)
	v_lshlrev_b32_e32 v208, 16, v79
	s_waitcnt lgkmcnt(2)
; DI float bf2f(unsigned short b) { return __uint_as_float(((unsigned)b) << 16); }
; DI float ex2(float x) { return __builtin_amdgcn_exp2f(x); }
; DI float rcpf_(float x) { return __builtin_amdgcn_rcpf(x); }
; DI void lru_tile(const Params& p, unsigned char* shm, int c, int nb, const LruPar par) {
;     ...
;         for (int rt = 0; rt < 8; ++rt) {
;             float av[4], bv[4];
; #pragma unroll
;             for (int jp = 0; jp < 2; ++jp) {
;                 const f32x2 xr = {acc[0][rt][2 * jp], acc[0][rt][2 * jp + 1]}, xi = {acc[1][rt][2 * jp], acc[1][rt][2 * jp + 1]};
;                 f32x2 er = xr * nl2 + nbr2, ei = xi * nl2 + nbi2;
;                 er = (f32x2){ex2(er[0]), ex2(er[1])} + one2; ei = (f32x2){ex2(ei[0]), ex2(ei[1])} + one2;
;                 const f32x2 r = {rcpf_(er[0]), rcpf_(er[1])}, ig = {rcpf_(ei[0]), rcpf_(ei[1])};
;                 const f32x2 la = r * cd2;
;                 const f32x2 a = {ex2(la[0]), ex2(la[1])};
;                 const f32x2 om = one2 - a * a;
;                 const f32x2 sc = {__builtin_amdgcn_sqrtf(om[0]), __builtin_amdgcn_sqrtf(om[1])};
;                 const f32x2 u2 = {bf2f(UB[(rt * 16 + 4 * q + 2 * jp) * LDU + chl]), bf2f(UB[(rt * 16 + 4 * q + 2 * jp + 1) * LDU + chl])};
;                 const f32x2 b2 = sc * ig * u2;
;                 av[2 * jp] = a[0]; av[2 * jp + 1] = a[1]; bv[2 * jp] = b2[0]; bv[2 * jp + 1] = b2[1];
;             }
;             float h = 0.f, P = 1.f;
;             if (d == 0) {
; #pragma unroll
;                 for (int j = 0; j < 4; ++j) { h = fmaf(av[j], h, bv[j]); P *= av[j]; hl[rt][j] = h; pc[rt][j] = P; }
;             } else {
; #pragma unroll
;                 for (int j = 3; j >= 0; --j) { h = fmaf(av[j], h, bv[j]); P *= av[j]; hl[rt][j] = h; pc[rt][j] = P; }
;             }
;             AG[(rt * 4 + q) * 16 + col] = (f32x2){P, h};
;             __builtin_amdgcn_sched_barrier(0);
	v_lshlrev_b32_e32 v209, 16, v81
	v_pk_mul_f32 v[172:173], v[172:173], v[174:175]
	v_pk_add_f32 v[174:175], v[176:177], 1.0 op_sel_hi:[1,0]
	v_pk_fma_f32 v[176:177], v[244:245], s[50:51], v[86:87] op_sel:[0,0,1] op_sel_hi:[1,0,1] neg_lo:[1,0,0] neg_hi:[1,0,0]
	v_rcp_f32_e32 v174, v174
	v_rcp_f32_e32 v175, v175
	v_exp_f32_e32 v176, v176
	v_exp_f32_e32 v177, v177
	v_pk_mul_f32 v[172:173], v[172:173], v[208:209]
	v_pk_mul_f32 v[174:175], v[92:93], v[174:175] op_sel:[1,0]
	v_fma_f32 v173, 0, v165, v173
	v_exp_f32_e32 v210, v174
	v_exp_f32_e32 v211, v175
	v_pk_add_f32 v[174:175], v[176:177], 1.0 op_sel_hi:[1,0]
	v_fmac_f32_e32 v172, v164, v173
	v_rcp_f32_e32 v174, v174
	v_pk_fma_f32 v[176:177], v[210:211], v[210:211], 1.0 op_sel_hi:[1,1,0] neg_lo:[1,0,0] neg_hi:[1,0,0]
	v_rcp_f32_e32 v175, v175
	v_sqrt_f32_e32 v176, v176
	v_sqrt_f32_e32 v177, v177
	v_mul_f32_e32 v164, v165, v164
	v_mul_f32_e32 v208, v211, v164
	v_pk_mul_f32 v[174:175], v[174:175], v[176:177]
	s_waitcnt lgkmcnt(0)
	v_lshlrev_b32_e32 v176, 16, v91
	v_lshlrev_b32_e32 v177, 16, v85
	v_pk_mul_f32 v[174:175], v[174:175], v[176:177]
	v_mul_f32_e32 v176, v210, v208
	v_fma_f32 v175, v211, v172, v175
	v_fmac_f32_e32 v174, v210, v175
	v_mov_b32_e32 v177, v174
	ds_write_b64 v61, v[176:177] offset:512
	v_pk_fma_f32 v[46:47], v[46:47], s[50:51], v[82:83] op_sel:[0,0,1] op_sel_hi:[1,0,1] neg_lo:[1,0,0] neg_hi:[1,0,0]
	v_pk_fma_f32 v[42:43], v[42:43], s[50:51], v[86:87] op_sel:[0,0,1] op_sel_hi:[1,0,1] neg_lo:[1,0,0] neg_hi:[1,0,0]
	v_exp_f32_e32 v46, v46
	v_exp_f32_e32 v47, v47
	v_pk_fma_f32 v[44:45], v[44:45], s[50:51], v[82:83] op_sel:[0,0,1] op_sel_hi:[1,0,1] neg_lo:[1,0,0] neg_hi:[1,0,0]
	v_exp_f32_e32 v210, v42
	v_exp_f32_e32 v211, v43
	v_pk_add_f32 v[46:47], v[46:47], 1.0 op_sel_hi:[1,0]
	v_exp_f32_e32 v44, v44
	v_rcp_f32_e32 v46, v46
	v_rcp_f32_e32 v47, v47
	v_exp_f32_e32 v45, v45
	v_pk_fma_f32 v[40:41], v[40:41], s[50:51], v[86:87] op_sel:[0,0,1] op_sel_hi:[1,0,1] neg_lo:[1,0,0] neg_hi:[1,0,0]
	ds_read_u16 v79, v68 offset:9248
	ds_read_u16 v81, v97 offset:9520
	v_pk_mul_f32 v[42:43], v[92:93], v[46:47] op_sel:[1,0]
	v_pk_add_f32 v[44:45], v[44:45], 1.0 op_sel_hi:[1,0]
	v_exp_f32_e32 v43, v43
	v_exp_f32_e32 v42, v42
	v_pk_add_f32 v[46:47], v[210:211], 1.0 op_sel_hi:[1,0]
	v_rcp_f32_e32 v44, v44
	v_rcp_f32_e32 v45, v45
	v_pk_fma_f32 v[210:211], v[42:43], v[42:43], 1.0 op_sel_hi:[1,1,0] neg_lo:[1,0,0] neg_hi:[1,0,0]
	v_rcp_f32_e32 v46, v46
	v_rcp_f32_e32 v47, v47
	v_sqrt_f32_e32 v210, v210
	v_sqrt_f32_e32 v211, v211
	v_exp_f32_e32 v40, v40
	v_exp_f32_e32 v41, v41
	v_pk_mul_f32 v[44:45], v[92:93], v[44:45] op_sel:[1,0]
	v_pk_mul_f32 v[46:47], v[46:47], v[210:211]
	v_exp_f32_e32 v210, v44
	v_exp_f32_e32 v211, v45
	v_pk_add_f32 v[40:41], v[40:41], 1.0 op_sel_hi:[1,0]
	ds_read_u16 v85, v97 offset:8976
	ds_read_u16 v91, v68 offset:8704
	v_rcp_f32_e32 v44, v40
	v_rcp_f32_e32 v45, v41
	v_pk_fma_f32 v[40:41], v[210:211], v[210:211], 1.0 op_sel_hi:[1,1,0] neg_lo:[1,0,0] neg_hi:[1,0,0]
	s_nop 0
	v_sqrt_f32_e32 v212, v40
	v_sqrt_f32_e32 v213, v41
	s_waitcnt lgkmcnt(3)
	v_lshlrev_b32_e32 v40, 16, v79
	s_waitcnt lgkmcnt(2)
	v_lshlrev_b32_e32 v41, 16, v81
	v_pk_mul_f32 v[40:41], v[46:47], v[40:41]
	v_pk_mul_f32 v[44:45], v[44:45], v[212:213]
	s_waitcnt lgkmcnt(0)
	v_lshlrev_b32_e32 v46, 16, v91
	v_lshlrev_b32_e32 v47, 16, v85
	v_fma_f32 v41, 0, v43, v41
	v_pk_mul_f32 v[44:45], v[44:45], v[46:47]
	v_fmac_f32_e32 v40, v42, v41
	v_mul_f32_e32 v42, v43, v42
	v_fma_f32 v45, v211, v40, v45
	v_mul_f32_e32 v209, v211, v42
	v_fmac_f32_e32 v44, v210, v45
	v_mul_f32_e32 v46, v210, v209
	v_mov_b32_e32 v47, v44
	ds_write_b64 v61, v[46:47] offset:1024
	v_pk_fma_f32 v[38:39], v[38:39], s[50:51], v[82:83] op_sel:[0,0,1] op_sel_hi:[1,0,1] neg_lo:[1,0,0] neg_hi:[1,0,0]
	v_pk_fma_f32 v[36:37], v[36:37], s[50:51], v[82:83] op_sel:[0,0,1] op_sel_hi:[1,0,1] neg_lo:[1,0,0] neg_hi:[1,0,0]
	v_exp_f32_e32 v38, v38
	v_exp_f32_e32 v39, v39
	v_exp_f32_e32 v36, v36
	v_exp_f32_e32 v37, v37
	v_pk_fma_f32 v[34:35], v[34:35], s[50:51], v[86:87] op_sel:[0,0,1] op_sel_hi:[1,0,1] neg_lo:[1,0,0] neg_hi:[1,0,0]
	v_pk_add_f32 v[38:39], v[38:39], 1.0 op_sel_hi:[1,0]
	v_exp_f32_e32 v210, v34
	v_rcp_f32_e32 v38, v38
	v_rcp_f32_e32 v39, v39
	v_pk_add_f32 v[36:37], v[36:37], 1.0 op_sel_hi:[1,0]
	v_exp_f32_e32 v211, v35
	v_rcp_f32_e32 v36, v36
	v_pk_mul_f32 v[34:35], v[92:93], v[38:39] op_sel:[1,0]
	v_rcp_f32_e32 v37, v37
	v_exp_f32_e32 v35, v35
	v_exp_f32_e32 v34, v34
	v_pk_fma_f32 v[32:33], v[32:33], s[50:51], v[86:87] op_sel:[0,0,1] op_sel_hi:[1,0,1] neg_lo:[1,0,0] neg_hi:[1,0,0]
	v_pk_mul_f32 v[36:37], v[92:93], v[36:37] op_sel:[1,0]
	v_exp_f32_e32 v32, v32
	v_exp_f32_e32 v33, v33
	v_pk_add_f32 v[38:39], v[210:211], 1.0 op_sel_hi:[1,0]
	v_pk_fma_f32 v[210:211], v[34:35], v[34:35], 1.0 op_sel_hi:[1,1,0] neg_lo:[1,0,0] neg_hi:[1,0,0]
	v_exp_f32_e32 v212, v36
	v_exp_f32_e32 v213, v37
	v_rcp_f32_e32 v38, v38
	v_rcp_f32_e32 v39, v39
	v_sqrt_f32_e32 v210, v210
	v_sqrt_f32_e32 v211, v211
	ds_read_u16 v47, v68 offset:13600
	ds_read_u16 v79, v97 offset:13872
	v_pk_add_f32 v[32:33], v[32:33], 1.0 op_sel_hi:[1,0]
	ds_read_u16 v81, v97 offset:13328
	ds_read_u16 v85, v68 offset:13056
	v_rcp_f32_e32 v36, v32
	v_rcp_f32_e32 v37, v33
	v_pk_fma_f32 v[32:33], v[212:213], v[212:213], 1.0 op_sel_hi:[1,1,0] neg_lo:[1,0,0] neg_hi:[1,0,0]
	v_pk_mul_f32 v[38:39], v[38:39], v[210:211]
	v_sqrt_f32_e32 v210, v32
	v_sqrt_f32_e32 v211, v33
	s_waitcnt lgkmcnt(3)
	v_lshlrev_b32_e32 v32, 16, v47
	s_waitcnt lgkmcnt(2)
	v_lshlrev_b32_e32 v33, 16, v79
	v_pk_mul_f32 v[32:33], v[38:39], v[32:33]
	v_pk_mul_f32 v[36:37], v[36:37], v[210:211]
	s_waitcnt lgkmcnt(0)
; DI float bf2f(unsigned short b) { return __uint_as_float(((unsigned)b) << 16); }
; DI float ex2(float x) { return __builtin_amdgcn_exp2f(x); }
; DI float rcpf_(float x) { return __builtin_amdgcn_rcpf(x); }
; DI void lru_tile(const Params& p, unsigned char* shm, int c, int nb, const LruPar par) {
;     ...
;         for (int rt = 0; rt < 8; ++rt) {
;             float av[4], bv[4];
; #pragma unroll
;             for (int jp = 0; jp < 2; ++jp) {
;                 const f32x2 xr = {acc[0][rt][2 * jp], acc[0][rt][2 * jp + 1]}, xi = {acc[1][rt][2 * jp], acc[1][rt][2 * jp + 1]};
;                 f32x2 er = xr * nl2 + nbr2, ei = xi * nl2 + nbi2;
;                 er = (f32x2){ex2(er[0]), ex2(er[1])} + one2; ei = (f32x2){ex2(ei[0]), ex2(ei[1])} + one2;
;                 const f32x2 r = {rcpf_(er[0]), rcpf_(er[1])}, ig = {rcpf_(ei[0]), rcpf_(ei[1])};
;                 const f32x2 la = r * cd2;
;                 const f32x2 a = {ex2(la[0]), ex2(la[1])};
;                 const f32x2 om = one2 - a * a;
;                 const f32x2 sc = {__builtin_amdgcn_sqrtf(om[0]), __builtin_amdgcn_sqrtf(om[1])};
;                 const f32x2 u2 = {bf2f(UB[(rt * 16 + 4 * q + 2 * jp) * LDU + chl]), bf2f(UB[(rt * 16 + 4 * q + 2 * jp + 1) * LDU + chl])};
;                 const f32x2 b2 = sc * ig * u2;
;                 av[2 * jp] = a[0]; av[2 * jp + 1] = a[1]; bv[2 * jp] = b2[0]; bv[2 * jp + 1] = b2[1];
;             }
;             float h = 0.f, P = 1.f;
;             if (d == 0) {
; #pragma unroll
;                 for (int j = 0; j < 4; ++j) { h = fmaf(av[j], h, bv[j]); P *= av[j]; hl[rt][j] = h; pc[rt][j] = P; }
;             } else {
; #pragma unroll
;                 for (int j = 3; j >= 0; --j) { h = fmaf(av[j], h, bv[j]); P *= av[j]; hl[rt][j] = h; pc[rt][j] = P; }
;             }
;             AG[(rt * 4 + q) * 16 + col] = (f32x2){P, h};
	v_lshlrev_b32_e32 v38, 16, v85
	v_lshlrev_b32_e32 v39, 16, v81
	v_fma_f32 v33, 0, v35, v33
	v_pk_mul_f32 v[36:37], v[36:37], v[38:39]
	v_fmac_f32_e32 v32, v34, v33
	v_mul_f32_e32 v34, v35, v34
	v_fma_f32 v37, v213, v32, v37
	v_mul_f32_e32 v210, v213, v34
	v_fmac_f32_e32 v36, v212, v37
	v_mul_f32_e32 v38, v212, v210
	v_mov_b32_e32 v39, v36
	ds_write_b64 v61, v[38:39] offset:1536
	v_pk_fma_f32 v[30:31], v[30:31], s[50:51], v[82:83] op_sel:[0,0,1] op_sel_hi:[1,0,1] neg_lo:[1,0,0] neg_hi:[1,0,0]
	v_pk_fma_f32 v[26:27], v[26:27], s[50:51], v[86:87] op_sel:[0,0,1] op_sel_hi:[1,0,1] neg_lo:[1,0,0] neg_hi:[1,0,0]
	v_exp_f32_e32 v30, v30
	v_exp_f32_e32 v31, v31
	v_pk_fma_f32 v[28:29], v[28:29], s[50:51], v[82:83] op_sel:[0,0,1] op_sel_hi:[1,0,1] neg_lo:[1,0,0] neg_hi:[1,0,0]
	v_exp_f32_e32 v212, v26
	v_exp_f32_e32 v213, v27
	v_pk_add_f32 v[30:31], v[30:31], 1.0 op_sel_hi:[1,0]
	v_exp_f32_e32 v28, v28
	v_rcp_f32_e32 v30, v30
	v_rcp_f32_e32 v31, v31
	v_exp_f32_e32 v29, v29
	v_pk_fma_f32 v[24:25], v[24:25], s[50:51], v[86:87] op_sel:[0,0,1] op_sel_hi:[1,0,1] neg_lo:[1,0,0] neg_hi:[1,0,0]
	ds_read_u16 v39, v68 offset:17952
	ds_read_u16 v47, v97 offset:18224
	v_pk_mul_f32 v[26:27], v[92:93], v[30:31] op_sel:[1,0]
	v_pk_add_f32 v[28:29], v[28:29], 1.0 op_sel_hi:[1,0]
	v_exp_f32_e32 v27, v27
	v_exp_f32_e32 v26, v26
	v_pk_add_f32 v[30:31], v[212:213], 1.0 op_sel_hi:[1,0]
	v_rcp_f32_e32 v28, v28
	v_rcp_f32_e32 v29, v29
	v_pk_fma_f32 v[212:213], v[26:27], v[26:27], 1.0 op_sel_hi:[1,1,0] neg_lo:[1,0,0] neg_hi:[1,0,0]
	v_rcp_f32_e32 v30, v30
	v_rcp_f32_e32 v31, v31
	v_sqrt_f32_e32 v212, v212
	v_sqrt_f32_e32 v213, v213
	v_exp_f32_e32 v24, v24
	v_exp_f32_e32 v25, v25
	v_pk_mul_f32 v[28:29], v[92:93], v[28:29] op_sel:[1,0]
	v_pk_mul_f32 v[30:31], v[30:31], v[212:213]
	v_exp_f32_e32 v212, v28
	v_exp_f32_e32 v213, v29
	v_pk_add_f32 v[24:25], v[24:25], 1.0 op_sel_hi:[1,0]
	ds_read_u16 v79, v97 offset:17680
	ds_read_u16 v81, v68 offset:17408
	v_rcp_f32_e32 v28, v24
	v_rcp_f32_e32 v29, v25
	v_pk_fma_f32 v[24:25], v[212:213], v[212:213], 1.0 op_sel_hi:[1,1,0] neg_lo:[1,0,0] neg_hi:[1,0,0]
	s_nop 0
	v_sqrt_f32_e32 v214, v24
	v_sqrt_f32_e32 v215, v25
	s_waitcnt lgkmcnt(3)
	v_lshlrev_b32_e32 v24, 16, v39
	s_waitcnt lgkmcnt(2)
	v_lshlrev_b32_e32 v25, 16, v47
	v_pk_mul_f32 v[24:25], v[30:31], v[24:25]
	v_pk_mul_f32 v[28:29], v[28:29], v[214:215]
	s_waitcnt lgkmcnt(0)
	v_lshlrev_b32_e32 v30, 16, v81
	v_lshlrev_b32_e32 v31, 16, v79
	v_fma_f32 v25, 0, v27, v25
	v_pk_mul_f32 v[28:29], v[28:29], v[30:31]
	v_fmac_f32_e32 v24, v26, v25
	v_mul_f32_e32 v26, v27, v26
	v_fma_f32 v29, v213, v24, v29
	v_mul_f32_e32 v211, v213, v26
	v_fmac_f32_e32 v28, v212, v29
	v_mul_f32_e32 v30, v212, v211
	v_mov_b32_e32 v31, v28
	ds_write_b64 v61, v[30:31] offset:2048
	v_pk_fma_f32 v[22:23], v[22:23], s[50:51], v[82:83] op_sel:[0,0,1] op_sel_hi:[1,0,1] neg_lo:[1,0,0] neg_hi:[1,0,0]
	v_pk_fma_f32 v[20:21], v[20:21], s[50:51], v[82:83] op_sel:[0,0,1] op_sel_hi:[1,0,1] neg_lo:[1,0,0] neg_hi:[1,0,0]
	v_exp_f32_e32 v22, v22
	v_exp_f32_e32 v23, v23
	v_exp_f32_e32 v20, v20
	v_exp_f32_e32 v21, v21
	v_pk_fma_f32 v[18:19], v[18:19], s[50:51], v[86:87] op_sel:[0,0,1] op_sel_hi:[1,0,1] neg_lo:[1,0,0] neg_hi:[1,0,0]
	v_pk_add_f32 v[22:23], v[22:23], 1.0 op_sel_hi:[1,0]
	v_exp_f32_e32 v212, v18
	v_rcp_f32_e32 v22, v22
	v_rcp_f32_e32 v23, v23
	v_pk_add_f32 v[20:21], v[20:21], 1.0 op_sel_hi:[1,0]
	v_exp_f32_e32 v213, v19
	v_rcp_f32_e32 v20, v20
	v_pk_mul_f32 v[18:19], v[92:93], v[22:23] op_sel:[1,0]
	v_rcp_f32_e32 v21, v21
	v_exp_f32_e32 v19, v19
	v_exp_f32_e32 v18, v18
	v_pk_fma_f32 v[16:17], v[16:17], s[50:51], v[86:87] op_sel:[0,0,1] op_sel_hi:[1,0,1] neg_lo:[1,0,0] neg_hi:[1,0,0]
	v_pk_mul_f32 v[20:21], v[92:93], v[20:21] op_sel:[1,0]
	v_exp_f32_e32 v16, v16
	v_exp_f32_e32 v17, v17
	v_pk_add_f32 v[22:23], v[212:213], 1.0 op_sel_hi:[1,0]
	v_pk_fma_f32 v[212:213], v[18:19], v[18:19], 1.0 op_sel_hi:[1,1,0] neg_lo:[1,0,0] neg_hi:[1,0,0]
	v_exp_f32_e32 v214, v20
	v_exp_f32_e32 v215, v21
	v_rcp_f32_e32 v22, v22
	v_rcp_f32_e32 v23, v23
	v_sqrt_f32_e32 v212, v212
	v_sqrt_f32_e32 v213, v213
	ds_read_u16 v31, v68 offset:22304
	ds_read_u16 v39, v97 offset:22576
	v_pk_add_f32 v[16:17], v[16:17], 1.0 op_sel_hi:[1,0]
	ds_read_u16 v47, v97 offset:22032
	ds_read_u16 v79, v68 offset:21760
	v_rcp_f32_e32 v20, v16
	v_rcp_f32_e32 v21, v17
	v_pk_fma_f32 v[16:17], v[214:215], v[214:215], 1.0 op_sel_hi:[1,1,0] neg_lo:[1,0,0] neg_hi:[1,0,0]
	v_pk_mul_f32 v[22:23], v[22:23], v[212:213]
	v_sqrt_f32_e32 v212, v16
	v_sqrt_f32_e32 v213, v17
	s_waitcnt lgkmcnt(3)
	v_lshlrev_b32_e32 v16, 16, v31
	s_waitcnt lgkmcnt(2)
	v_lshlrev_b32_e32 v17, 16, v39
	v_pk_mul_f32 v[16:17], v[22:23], v[16:17]
	v_pk_mul_f32 v[20:21], v[20:21], v[212:213]
	s_waitcnt lgkmcnt(0)
; DI float bf2f(unsigned short b) { return __uint_as_float(((unsigned)b) << 16); }
; DI float ex2(float x) { return __builtin_amdgcn_exp2f(x); }
; DI float rcpf_(float x) { return __builtin_amdgcn_rcpf(x); }
; DI void lru_tile(const Params& p, unsigned char* shm, int c, int nb, const LruPar par) {
;     ...
;         for (int rt = 0; rt < 8; ++rt) {
;             float av[4], bv[4];
; #pragma unroll
;             for (int jp = 0; jp < 2; ++jp) {
;                 const f32x2 xr = {acc[0][rt][2 * jp], acc[0][rt][2 * jp + 1]}, xi = {acc[1][rt][2 * jp], acc[1][rt][2 * jp + 1]};
;                 f32x2 er = xr * nl2 + nbr2, ei = xi * nl2 + nbi2;
;                 er = (f32x2){ex2(er[0]), ex2(er[1])} + one2; ei = (f32x2){ex2(ei[0]), ex2(ei[1])} + one2;
;                 const f32x2 r = {rcpf_(er[0]), rcpf_(er[1])}, ig = {rcpf_(ei[0]), rcpf_(ei[1])};
;                 const f32x2 la = r * cd2;
;                 const f32x2 a = {ex2(la[0]), ex2(la[1])};
;                 const f32x2 om = one2 - a * a;
;                 const f32x2 sc = {__builtin_amdgcn_sqrtf(om[0]), __builtin_amdgcn_sqrtf(om[1])};
;                 const f32x2 u2 = {bf2f(UB[(rt * 16 + 4 * q + 2 * jp) * LDU + chl]), bf2f(UB[(rt * 16 + 4 * q + 2 * jp + 1) * LDU + chl])};
;                 const f32x2 b2 = sc * ig * u2;
;                 av[2 * jp] = a[0]; av[2 * jp + 1] = a[1]; bv[2 * jp] = b2[0]; bv[2 * jp + 1] = b2[1];
;             }
;             float h = 0.f, P = 1.f;
;             if (d == 0) {
; #pragma unroll
;                 for (int j = 0; j < 4; ++j) { h = fmaf(av[j], h, bv[j]); P *= av[j]; hl[rt][j] = h; pc[rt][j] = P; }
;             } else {
; #pragma unroll
;                 for (int j = 3; j >= 0; --j) { h = fmaf(av[j], h, bv[j]); P *= av[j]; hl[rt][j] = h; pc[rt][j] = P; }
;             }
;             AG[(rt * 4 + q) * 16 + col] = (f32x2){P, h};
;             __builtin_amdgcn_sched_barrier(0);
;         }
;         asm volatile("s_waitcnt lgkmcnt(0)" ::: "memory");
;         float carry[8], pref[8]; float cin = 0.f, pa = 1.f;
; #pragma unroll
;         for (int gi = 0; gi < 32; ++gi) {
;             const int G = d == 0 ? gi : 31 - gi; const int rt = G >> 2, qq = G & 3;
;             const f32x2 ah = AG[G * 16 + col];
	v_lshlrev_b32_e32 v22, 16, v79
	v_lshlrev_b32_e32 v23, 16, v47
	v_fma_f32 v17, 0, v19, v17
	v_pk_mul_f32 v[20:21], v[20:21], v[22:23]
	v_fmac_f32_e32 v16, v18, v17
	v_mul_f32_e32 v18, v19, v18
	v_fma_f32 v21, v215, v16, v21
	v_mul_f32_e32 v212, v215, v18
	v_fmac_f32_e32 v20, v214, v21
	v_mul_f32_e32 v22, v214, v212
	v_mov_b32_e32 v23, v20
	ds_write_b64 v61, v[22:23] offset:2560
	v_pk_fma_f32 v[14:15], v[14:15], s[50:51], v[82:83] op_sel:[0,0,1] op_sel_hi:[1,0,1] neg_lo:[1,0,0] neg_hi:[1,0,0]
	v_pk_fma_f32 v[10:11], v[10:11], s[50:51], v[86:87] op_sel:[0,0,1] op_sel_hi:[1,0,1] neg_lo:[1,0,0] neg_hi:[1,0,0]
	v_exp_f32_e32 v14, v14
	v_exp_f32_e32 v15, v15
	v_pk_fma_f32 v[12:13], v[12:13], s[50:51], v[82:83] op_sel:[0,0,1] op_sel_hi:[1,0,1] neg_lo:[1,0,0] neg_hi:[1,0,0]
	v_exp_f32_e32 v214, v10
	v_exp_f32_e32 v215, v11
	v_pk_add_f32 v[14:15], v[14:15], 1.0 op_sel_hi:[1,0]
	v_exp_f32_e32 v12, v12
	v_rcp_f32_e32 v14, v14
	v_rcp_f32_e32 v15, v15
	v_exp_f32_e32 v13, v13
	v_pk_fma_f32 v[8:9], v[8:9], s[50:51], v[86:87] op_sel:[0,0,1] op_sel_hi:[1,0,1] neg_lo:[1,0,0] neg_hi:[1,0,0]
	ds_read_u16 v23, v68 offset:26656
	ds_read_u16 v31, v97 offset:26928
	v_pk_mul_f32 v[10:11], v[92:93], v[14:15] op_sel:[1,0]
	v_pk_add_f32 v[12:13], v[12:13], 1.0 op_sel_hi:[1,0]
	v_exp_f32_e32 v11, v11
	v_exp_f32_e32 v10, v10
	v_pk_add_f32 v[14:15], v[214:215], 1.0 op_sel_hi:[1,0]
	v_rcp_f32_e32 v12, v12
	v_rcp_f32_e32 v13, v13
	v_pk_fma_f32 v[214:215], v[10:11], v[10:11], 1.0 op_sel_hi:[1,1,0] neg_lo:[1,0,0] neg_hi:[1,0,0]
	v_rcp_f32_e32 v14, v14
	v_rcp_f32_e32 v15, v15
	v_sqrt_f32_e32 v214, v214
	v_sqrt_f32_e32 v215, v215
	v_exp_f32_e32 v8, v8
	v_exp_f32_e32 v9, v9
	v_pk_mul_f32 v[12:13], v[92:93], v[12:13] op_sel:[1,0]
	v_pk_mul_f32 v[14:15], v[14:15], v[214:215]
	v_exp_f32_e32 v214, v12
	v_exp_f32_e32 v215, v13
	v_pk_add_f32 v[8:9], v[8:9], 1.0 op_sel_hi:[1,0]
	ds_read_u16 v39, v97 offset:26384
	ds_read_u16 v47, v68 offset:26112
	v_rcp_f32_e32 v12, v8
	v_rcp_f32_e32 v13, v9
	v_pk_fma_f32 v[8:9], v[214:215], v[214:215], 1.0 op_sel_hi:[1,1,0] neg_lo:[1,0,0] neg_hi:[1,0,0]
	s_nop 0
	v_sqrt_f32_e32 v216, v8
	v_sqrt_f32_e32 v217, v9
	s_waitcnt lgkmcnt(3)
	v_lshlrev_b32_e32 v8, 16, v23
	s_waitcnt lgkmcnt(2)
	v_lshlrev_b32_e32 v9, 16, v31
	v_pk_mul_f32 v[8:9], v[14:15], v[8:9]
	v_pk_mul_f32 v[12:13], v[12:13], v[216:217]
	s_waitcnt lgkmcnt(0)
	v_lshlrev_b32_e32 v14, 16, v47
	v_lshlrev_b32_e32 v15, 16, v39
	v_fma_f32 v9, 0, v11, v9
	v_pk_mul_f32 v[12:13], v[12:13], v[14:15]
	v_fmac_f32_e32 v8, v10, v9
	v_mul_f32_e32 v10, v11, v10
	v_fma_f32 v13, v215, v8, v13
	v_mul_f32_e32 v213, v215, v10
	v_fmac_f32_e32 v12, v214, v13
	v_mul_f32_e32 v14, v214, v213
	v_mov_b32_e32 v15, v12
	ds_write_b64 v61, v[14:15] offset:3072
	v_pk_fma_f32 v[6:7], v[6:7], s[50:51], v[82:83] op_sel:[0,0,1] op_sel_hi:[1,0,1] neg_lo:[1,0,0] neg_hi:[1,0,0]
	v_pk_fma_f32 v[4:5], v[4:5], s[50:51], v[82:83] op_sel:[0,0,1] op_sel_hi:[1,0,1] neg_lo:[1,0,0] neg_hi:[1,0,0]
	v_exp_f32_e32 v6, v6
	v_exp_f32_e32 v7, v7
	v_exp_f32_e32 v4, v4
	v_exp_f32_e32 v5, v5
	v_pk_fma_f32 v[2:3], v[2:3], s[50:51], v[86:87] op_sel:[0,0,1] op_sel_hi:[1,0,1] neg_lo:[1,0,0] neg_hi:[1,0,0]
	v_pk_add_f32 v[6:7], v[6:7], 1.0 op_sel_hi:[1,0]
	v_exp_f32_e32 v214, v2
	v_rcp_f32_e32 v6, v6
	v_rcp_f32_e32 v7, v7
	v_pk_add_f32 v[4:5], v[4:5], 1.0 op_sel_hi:[1,0]
	v_exp_f32_e32 v215, v3
	v_rcp_f32_e32 v4, v4
	v_pk_mul_f32 v[2:3], v[92:93], v[6:7] op_sel:[1,0]
	v_rcp_f32_e32 v5, v5
	v_exp_f32_e32 v3, v3
	v_exp_f32_e32 v2, v2
	v_pk_fma_f32 v[0:1], v[0:1], s[50:51], v[86:87] op_sel:[0,0,1] op_sel_hi:[1,0,1] neg_lo:[1,0,0] neg_hi:[1,0,0]
	v_pk_mul_f32 v[4:5], v[92:93], v[4:5] op_sel:[1,0]
	v_exp_f32_e32 v0, v0
	v_exp_f32_e32 v1, v1
	v_pk_add_f32 v[6:7], v[214:215], 1.0 op_sel_hi:[1,0]
	v_pk_fma_f32 v[214:215], v[2:3], v[2:3], 1.0 op_sel_hi:[1,1,0] neg_lo:[1,0,0] neg_hi:[1,0,0]
	v_exp_f32_e32 v216, v4
	v_exp_f32_e32 v217, v5
	v_rcp_f32_e32 v6, v6
	v_rcp_f32_e32 v7, v7
	v_sqrt_f32_e32 v214, v214
	v_sqrt_f32_e32 v215, v215
	ds_read_u16 v15, v68 offset:31008
	ds_read_u16 v23, v97 offset:31280
	v_pk_add_f32 v[0:1], v[0:1], 1.0 op_sel_hi:[1,0]
	ds_read_u16 v31, v97 offset:30736
	ds_read_u16 v39, v68 offset:30464
	v_rcp_f32_e32 v4, v0
	v_rcp_f32_e32 v5, v1
	v_pk_fma_f32 v[0:1], v[216:217], v[216:217], 1.0 op_sel_hi:[1,1,0] neg_lo:[1,0,0] neg_hi:[1,0,0]
	v_pk_mul_f32 v[6:7], v[6:7], v[214:215]
	v_sqrt_f32_e32 v214, v0
	v_sqrt_f32_e32 v215, v1
	s_waitcnt lgkmcnt(3)
	v_lshlrev_b32_e32 v0, 16, v15
	s_waitcnt lgkmcnt(2)
	v_lshlrev_b32_e32 v1, 16, v23
	v_pk_mul_f32 v[0:1], v[6:7], v[0:1]
	v_pk_mul_f32 v[4:5], v[4:5], v[214:215]
	s_waitcnt lgkmcnt(0)
	v_lshlrev_b32_e32 v6, 16, v39
	v_lshlrev_b32_e32 v7, 16, v31
	v_fma_f32 v1, 0, v3, v1
	v_pk_mul_f32 v[4:5], v[4:5], v[6:7]
	v_fmac_f32_e32 v0, v2, v1
	v_mul_f32_e32 v2, v3, v2
	v_fma_f32 v5, v217, v0, v5
	v_mul_f32_e32 v214, v217, v2
	v_fmac_f32_e32 v4, v216, v5
	v_mul_f32_e32 v6, v216, v214
	v_mov_b32_e32 v7, v4
	ds_write_b64 v61, v[6:7] offset:3584
	s_waitcnt lgkmcnt(0)
	ds_read_b64 v[220:221], v59 offset:3968
	ds_read2_b64 v[216:219], v89 offset0:208 offset1:224
	v_cndmask_b32_e64 v15, v77, 1.0, s[8:9]
	v_add_u32_e32 v85, 0x400, v59
	s_waitcnt lgkmcnt(1)
	v_fma_f32 v7, 0, v220, v221
	v_cndmask_b32_e64 v23, v15, v220, s[6:7]
	s_waitcnt lgkmcnt(0)
; DI void lru_tile(const Params& p, unsigned char* shm, int c, int nb, const LruPar par) {
;     ...
;         float carry[8], pref[8]; float cin = 0.f, pa = 1.f;
; #pragma unroll
;         for (int gi = 0; gi < 32; ++gi) {
;             const int G = d == 0 ? gi : 31 - gi; const int rt = G >> 2, qq = G & 3;
;             const f32x2 ah = AG[G * 16 + col];
;             if (qq == q) { carry[rt] = cin; pref[rt] = pa; }
;             cin = fmaf(ah[0], cin, ah[1]); pa *= ah[0];
;         }
;         if (q == 0) AGG[((size_t)d * 128 + c) * 2048 + chg] = (f32x2){pa, cin};
	v_pk_mul_f32 v[222:223], v[220:221], v[218:219]
	v_fma_f32 v15, v218, v7, v219
	ds_read2_b64 v[218:221], v89 offset0:176 offset1:192
	v_cndmask_b32_e64 v31, v23, v222, s[4:5]
	v_fma_f32 v23, v216, v15, v217
	v_pk_mul_f32 v[216:217], v[222:223], v[216:217]
	s_waitcnt lgkmcnt(0)
	v_fma_f32 v39, v220, v23, v221
	v_cndmask_b32_e64 v77, v31, v216, s[10:11]
	v_pk_mul_f32 v[216:217], v[216:217], v[220:221]
	ds_read2_b64 v[220:223], v89 offset0:144 offset1:160
	v_cndmask_b32_e64 v31, v191, v216, s[8:9]
	v_fma_f32 v47, v218, v39, v219
	v_pk_mul_f32 v[216:217], v[216:217], v[218:219]
	s_waitcnt lgkmcnt(0)
	v_fma_f32 v61, v222, v47, v223
	v_cndmask_b32_e64 v31, v31, v216, s[6:7]
	v_pk_mul_f32 v[222:223], v[216:217], v[222:223]
	ds_read2_b64 v[216:219], v89 offset0:112 offset1:128
	v_cndmask_b32_e64 v31, v31, v222, s[4:5]
	v_fma_f32 v97, v220, v61, v221
	v_pk_mul_f32 v[220:221], v[222:223], v[220:221]
	s_waitcnt lgkmcnt(0)
	v_fma_f32 v171, v218, v97, v219
	v_cndmask_b32_e64 v79, v31, v220, s[10:11]
	v_pk_mul_f32 v[222:223], v[220:221], v[218:219]
	ds_read2_b64 v[218:221], v89 offset0:80 offset1:96
	v_fma_f32 v177, v216, v171, v217
	v_pk_mul_f32 v[216:217], v[222:223], v[216:217]
	v_cndmask_b32_e64 v31, v182, v222, s[8:9]
	v_cndmask_b32_e64 v31, v31, v216, s[6:7]
	s_waitcnt lgkmcnt(0)
	v_fma_f32 v215, v220, v177, v221
	v_pk_mul_f32 v[224:225], v[216:217], v[220:221]
	ds_read2_b64 v[220:223], v89 offset0:48 offset1:64
	v_fma_f32 v216, v218, v215, v219
	v_pk_mul_f32 v[218:219], v[224:225], v[218:219]
	v_cndmask_b32_e64 v31, v31, v224, s[4:5]
	v_cndmask_b32_e64 v81, v31, v218, s[10:11]
	s_waitcnt lgkmcnt(0)
	v_fma_f32 v217, v222, v216, v223
	v_pk_mul_f32 v[226:227], v[218:219], v[222:223]
	ds_read2_b64 v[222:225], v89 offset0:16 offset1:32
	v_fma_f32 v218, v220, v217, v221
	v_pk_mul_f32 v[220:221], v[226:227], v[220:221]
	v_cndmask_b32_e64 v31, v117, v226, s[8:9]
	v_cndmask_b32_e64 v31, v31, v220, s[6:7]
	s_waitcnt lgkmcnt(0)
	v_fma_f32 v219, v224, v218, v225
	v_pk_mul_f32 v[228:229], v[220:221], v[224:225]
	ds_read2_b64 v[224:227], v85 offset0:112 offset1:128
	v_fma_f32 v220, v222, v219, v223
	v_pk_mul_f32 v[222:223], v[228:229], v[222:223]
	v_cndmask_b32_e64 v31, v31, v228, s[4:5]
	v_cndmask_b32_e64 v85, v31, v222, s[10:11]
	s_waitcnt lgkmcnt(0)
	v_fma_f32 v221, v226, v220, v227
	v_pk_mul_f32 v[230:231], v[222:223], v[226:227]
	ds_read2_b64 v[226:229], v59 offset0:208 offset1:224
	v_fma_f32 v222, v224, v221, v225
	v_pk_mul_f32 v[224:225], v[230:231], v[224:225]
	v_cndmask_b32_e64 v31, v109, v230, s[8:9]
	v_cndmask_b32_e64 v31, v31, v224, s[6:7]
	s_waitcnt lgkmcnt(0)
	v_fma_f32 v223, v228, v222, v229
	v_pk_mul_f32 v[232:233], v[224:225], v[228:229]
	ds_read2_b64 v[228:231], v59 offset0:176 offset1:192
	v_fma_f32 v224, v226, v223, v227
	v_pk_mul_f32 v[226:227], v[232:233], v[226:227]
	v_cndmask_b32_e64 v31, v31, v232, s[4:5]
	v_cndmask_b32_e64 v89, v31, v226, s[10:11]
	s_waitcnt lgkmcnt(0)
	v_fma_f32 v225, v230, v224, v231
	v_pk_mul_f32 v[234:235], v[226:227], v[230:231]
	ds_read2_b64 v[230:233], v59 offset0:144 offset1:160
	v_fma_f32 v226, v228, v225, v229
	v_pk_mul_f32 v[228:229], v[234:235], v[228:229]
	v_cndmask_b32_e64 v31, v107, v234, s[8:9]
	v_cndmask_b32_e64 v31, v31, v228, s[6:7]
	s_waitcnt lgkmcnt(0)
	v_fma_f32 v227, v232, v226, v233
	v_pk_mul_f32 v[236:237], v[228:229], v[232:233]
	ds_read2_b64 v[232:235], v59 offset0:112 offset1:128
	v_fma_f32 v228, v230, v227, v231
	v_pk_mul_f32 v[230:231], v[236:237], v[230:231]
	v_cndmask_b32_e64 v31, v31, v236, s[4:5]
	v_cndmask_b32_e64 v91, v31, v230, s[10:11]
	s_waitcnt lgkmcnt(0)
	v_fma_f32 v229, v234, v228, v235
	v_pk_mul_f32 v[238:239], v[230:231], v[234:235]
	ds_read2_b64 v[234:237], v59 offset0:80 offset1:96
	v_fma_f32 v230, v232, v229, v233
	v_pk_mul_f32 v[232:233], v[238:239], v[232:233]
	v_cndmask_b32_e64 v31, v99, v238, s[8:9]
	v_cndmask_b32_e64 v31, v31, v232, s[6:7]
	s_waitcnt lgkmcnt(0)
	v_fma_f32 v231, v236, v230, v237
	v_pk_mul_f32 v[240:241], v[232:233], v[236:237]
	ds_read2_b64 v[236:239], v59 offset0:48 offset1:64
	v_fma_f32 v232, v234, v231, v235
	v_pk_mul_f32 v[234:235], v[240:241], v[234:235]
	v_cndmask_b32_e64 v31, v31, v240, s[4:5]
	v_cndmask_b32_e64 v162, v31, v234, s[10:11]
	s_waitcnt lgkmcnt(0)
	v_fma_f32 v233, v238, v232, v239
	v_pk_mul_f32 v[242:243], v[234:235], v[238:239]
	ds_read2_b64 v[238:241], v59 offset0:16 offset1:32
	v_cndmask_b32_e64 v31, v178, v242, s[8:9]
	v_pk_mul_f32 v[178:179], v[242:243], v[236:237]
	v_fma_f32 v234, v236, v233, v237
	v_cndmask_b32_e64 v31, v31, v178, s[6:7]
	v_cndmask_b32_e64 v180, v242, v178, s[6:7]
	s_waitcnt lgkmcnt(0)
	v_pk_mul_f32 v[178:179], v[178:179], v[240:241]
	v_fma_f32 v235, v240, v234, v241
	v_cndmask_b32_e64 v237, v31, v178, s[4:5]
	v_cndmask_b32_e64 v31, v180, v178, s[4:5]
	v_pk_mul_f32 v[178:179], v[178:179], v[238:239]
	v_fma_f32 v236, v238, v235, v239
	v_cndmask_b32_e64 v180, v237, v178, s[10:11]
	s_and_saveexec_b64 s[60:61], s[10:11]
	s_cbranch_execz .LBB0_211
	ds_read_b64 v[238:239], v59
	v_add_co_u32_e32 v56, vcc, 0x200000, v56
	v_mov_b32_e32 v31, v180
	s_nop 0
	v_addc_co_u32_e32 v57, vcc, 0, v57, vcc
	s_waitcnt lgkmcnt(0)
	v_pk_mul_f32 v[178:179], v[178:179], v[238:239]
	v_fmac_f32_e32 v239, v238, v236
	v_mov_b32_e32 v179, v239
	global_store_dwordx2 v[56:57], v[178:179], off
	s_branch .LBB0_211
